# mixer-B loop v3 with >=12 wait states between the last QK MFMA and the first VALU read on every path
# baseline (speedup 1.0000x reference)
; #define LAS __attribute__((address_space(3)))
; __device__ __forceinline__ void partialSM(f32x16& p0, f32x16& p1, const LAS float* tbp, int relc, float cL, float cR, float& m_reg, float& mn, float& alpha) {
;     float cb = 0.f;
;     if (relc + 63 <= -559) cb = cL;
;     else if (relc - 31 >= 559) cb = cR;
;     else {
; #pragma unroll
;         for (int r = 0; r < 16; ++r) { p0[r] += tbp[(r & 3) + 8 * (r >> 2)]; p1[r] += tbp[32 + (r & 3) + 8 * (r >> 2)]; }
;     }
;     float pmax = p0[0];
; #pragma unroll
;     for (int r = 1; r < 16; ++r) pmax = fmaxf(pmax, p0[r]);
; #pragma unroll
;     for (int r = 0; r < 16; ++r) pmax = fmaxf(pmax, p1[r]);
;     pmax = half_max(pmax) + cb;
;     if (__builtin_expect(__all(pmax - m_reg <= 8.f), 1)) { mn = m_reg; alpha = 1.f; }
;     else { mn = fmaxf(m_reg, pmax); alpha = __builtin_amdgcn_exp2f(m_reg - mn); m_reg = mn; }
;     const float sh = mn - cb;
; #pragma unroll
;     for (int r = 0; r < 16; ++r) { p0[r] -= sh; p1[r] -= sh; }
; #pragma unroll
;     for (int r = 0; r < 16; ++r) p0[r] = __builtin_amdgcn_exp2f(p0[r]);
; }
; template <int D0> __device__ __forceinline__ void pv_one(f32x16& od, int vb, bf16x8 pa0, bf16x8 pa1, bf16x8 pa2, bf16x8 pa3) {
;     s16x4 l0 = tr_read<v_rd_off(D0, 0, 0)>(vb), h0 = tr_read<v_rd_off(D0, 0, 1)>(vb), l1 = tr_read<v_rd_off(D0, 1, 0)>(vb), h1 = tr_read<v_rd_off(D0, 1, 1)>(vb);
;     s16x4 l2 = tr_read<v_rd_off(D0, 2, 0)>(vb), h2 = tr_read<v_rd_off(D0, 2, 1)>(vb), l3 = tr_read<v_rd_off(D0, 3, 0)>(vb), h3 = tr_read<v_rd_off(D0, 3, 1)>(vb);
;     asm volatile("s_waitcnt lgkmcnt(0)" : "+v"(l0), "+v"(h0), "+v"(l1), "+v"(h1), "+v"(l2), "+v"(h2), "+v"(l3), "+v"(h3) :: "memory");
;     od = __builtin_amdgcn_mfma_f32_32x32x16_bf16(pa0, PKV(l0, h0), od, 0, 0, 0);
;     od = __builtin_amdgcn_mfma_f32_32x32x16_bf16(pa1, PKV(l1, h1), od, 0, 0, 0);
;     od = __builtin_amdgcn_mfma_f32_32x32x16_bf16(pa2, PKV(l2, h2), od, 0, 0, 0);
;     od = __builtin_amdgcn_mfma_f32_32x32x16_bf16(pa3, PKV(l3, h3), od, 0, 0, 0);
; }
; __device__ __forceinline__ void pv_d0(f32x16* o, int vb, bf16x8 pa0, bf16x8 pa1, bf16x8 pa2, bf16x8 pa3) {
;     pv_one<0>(o[0], vb, pa0, pa1, pa2, pa3); pv_one<1>(o[1], vb, pa0, pa1, pa2, pa3); pv_one<2>(o[2], vb, pa0, pa1, pa2, pa3); pv_one<3>(o[3], vb, pa0, pa1, pa2, pa3);
; }
.Lmb_pv_h1:
	s_waitcnt lgkmcnt(0)
	v_mfma_f32_32x32x16_bf16 v[0:15], v[232:235], v[240:243], v[0:15]
	ds_read_b64_tr_b16 v[240:241], v175 offset:512
	ds_read_b64_tr_b16 v[242:243], v175 offset:2560
	v_mfma_f32_32x32x16_bf16 v[0:15], v[236:239], v[244:247], v[0:15]
	ds_read_b64_tr_b16 v[244:245], v175 offset:4608
	ds_read_b64_tr_b16 v[246:247], v175 offset:6656
	v_max3_f32 v254, v80, v81, v82
	v_max3_f32 v255, v83, v84, v85
	v_max3_f32 v254, v254, v86, v87
	v_max3_f32 v255, v255, v88, v89
	v_max3_f32 v254, v254, v90, v91
	v_max3_f32 v255, v255, v92, v93
	v_mfma_f32_32x32x16_bf16 v[0:15], v[144:147], v[152:155], v[0:15]
	ds_read_b64_tr_b16 v[152:153], v175 offset:8704
	ds_read_b64_tr_b16 v[154:155], v175 offset:10752
	v_max3_f32 v254, v254, v94, v95
	v_max3_f32 v255, v255, v64, v65
	v_max3_f32 v254, v254, v66, v67
	v_max3_f32 v255, v255, v68, v69
	v_max3_f32 v254, v254, v70, v71
	v_max3_f32 v255, v255, v72, v73
	v_mfma_f32_32x32x16_bf16 v[0:15], v[148:151], v[156:159], v[0:15]
	ds_read_b64_tr_b16 v[156:157], v175 offset:12800
	ds_read_b64_tr_b16 v[158:159], v175 offset:14848
	v_max3_f32 v254, v254, v74, v75
	v_max3_f32 v255, v255, v76, v77
	v_max3_f32 v254, v254, v78, v79
	v_max_f32_e32 v254, v254, v255
	v_mov_b32_e32 v255, v254
	s_waitcnt lgkmcnt(0)
	v_mfma_f32_32x32x16_bf16 v[48:63], v[232:235], v[240:243], v[48:63]
	ds_read_b64_tr_b16 v[240:241], v175 offset:1024
	ds_read_b64_tr_b16 v[242:243], v175 offset:3072
	v_permlane32_swap_b32_e32 v254, v255
	v_max_f32_e32 v254, v254, v255
	v_add_f32_e32 v254, v249, v254
	v_sub_f32_e32 v255, v254, v250
	v_cmp_ge_f32_e32 vcc, s35, v255
	v_max_f32_e32 v255, v250, v254
	v_mfma_f32_32x32x16_bf16 v[48:63], v[236:239], v[244:247], v[48:63]
	ds_read_b64_tr_b16 v[244:245], v175 offset:5120
	ds_read_b64_tr_b16 v[246:247], v175 offset:7168
	v_sub_f32_e32 v248, v250, v255
	v_exp_f32_e32 v248, v248
	v_sub_f32_e32 v252, v255, v249
	v_sub_f32_e32 v254, v250, v249
	s_cmp_eq_u64 vcc, exec
	s_cselect_b64 s[4:5], -1, 0
	v_cndmask_b32_e64 v251, v248, 1.0, s[4:5]
	v_mfma_f32_32x32x16_bf16 v[48:63], v[144:147], v[152:155], v[48:63]
	ds_read_b64_tr_b16 v[152:153], v175 offset:9216
	ds_read_b64_tr_b16 v[154:155], v175 offset:11264
	v_cndmask_b32_e64 v250, v255, v250, s[4:5]
	v_cndmask_b32_e64 v252, v252, v254, s[4:5]
	v_sub_f32_e32 v80, v80, v252
	v_sub_f32_e32 v81, v81, v252
	v_sub_f32_e32 v82, v82, v252
	v_sub_f32_e32 v83, v83, v252
	v_mfma_f32_32x32x16_bf16 v[48:63], v[148:151], v[156:159], v[48:63]
	ds_read_b64_tr_b16 v[156:157], v175 offset:13312
	ds_read_b64_tr_b16 v[158:159], v175 offset:15360
	v_sub_f32_e32 v84, v84, v252
	v_sub_f32_e32 v85, v85, v252
	v_sub_f32_e32 v86, v86, v252
	v_sub_f32_e32 v87, v87, v252
	v_sub_f32_e32 v88, v88, v252
	v_sub_f32_e32 v89, v89, v252
	s_waitcnt lgkmcnt(0)
	v_mfma_f32_32x32x16_bf16 v[32:47], v[232:235], v[240:243], v[32:47]
	ds_read_b64_tr_b16 v[240:241], v175 offset:1536
	ds_read_b64_tr_b16 v[242:243], v175 offset:3584
	v_sub_f32_e32 v90, v90, v252
	v_sub_f32_e32 v91, v91, v252
	v_sub_f32_e32 v92, v92, v252
	v_sub_f32_e32 v93, v93, v252
	v_sub_f32_e32 v94, v94, v252
	v_sub_f32_e32 v95, v95, v252
	v_mfma_f32_32x32x16_bf16 v[32:47], v[236:239], v[244:247], v[32:47]
	ds_read_b64_tr_b16 v[244:245], v175 offset:5632
	ds_read_b64_tr_b16 v[246:247], v175 offset:7680
	v_exp_f32_e32 v80, v80
	v_sub_f32_e32 v64, v64, v252
	v_exp_f32_e32 v81, v81
	v_sub_f32_e32 v65, v65, v252
	v_mfma_f32_32x32x16_bf16 v[32:47], v[144:147], v[152:155], v[32:47]
	ds_read_b64_tr_b16 v[152:153], v175 offset:9728
	ds_read_b64_tr_b16 v[154:155], v175 offset:11776
	v_exp_f32_e32 v82, v82
	v_sub_f32_e32 v66, v66, v252
	v_exp_f32_e32 v83, v83
	v_sub_f32_e32 v67, v67, v252
	v_mfma_f32_32x32x16_bf16 v[32:47], v[148:151], v[156:159], v[32:47]
	ds_read_b64_tr_b16 v[156:157], v175 offset:13824
	ds_read_b64_tr_b16 v[158:159], v175 offset:15872
	v_exp_f32_e32 v84, v84
	v_sub_f32_e32 v68, v68, v252
	v_exp_f32_e32 v85, v85
	v_sub_f32_e32 v69, v69, v252
	s_waitcnt lgkmcnt(0)
	v_mfma_f32_32x32x16_bf16 v[16:31], v[232:235], v[240:243], v[16:31]
	v_exp_f32_e32 v86, v86
	v_sub_f32_e32 v70, v70, v252
	v_exp_f32_e32 v87, v87
	v_sub_f32_e32 v71, v71, v252
	v_mfma_f32_32x32x16_bf16 v[16:31], v[236:239], v[244:247], v[16:31]
	v_exp_f32_e32 v88, v88
	v_sub_f32_e32 v72, v72, v252
	v_exp_f32_e32 v89, v89
	v_sub_f32_e32 v73, v73, v252
	v_mfma_f32_32x32x16_bf16 v[16:31], v[144:147], v[152:155], v[16:31]
	v_exp_f32_e32 v90, v90
	v_sub_f32_e32 v74, v74, v252
	v_exp_f32_e32 v91, v91
	v_sub_f32_e32 v75, v75, v252
	v_mfma_f32_32x32x16_bf16 v[16:31], v[148:151], v[156:159], v[16:31]
	v_exp_f32_e32 v92, v92
	v_sub_f32_e32 v76, v76, v252
	v_exp_f32_e32 v93, v93
	v_sub_f32_e32 v77, v77, v252
	v_exp_f32_e32 v94, v94
	v_sub_f32_e32 v78, v78, v252
	v_exp_f32_e32 v95, v95
	v_sub_f32_e32 v79, v79, v252
	s_barrier
	s_waitcnt vmcnt(4)
	s_and_b64 vcc, exec, s[26:27]
	s_cbranch_vccz .Lmb_w1
	s_waitcnt vmcnt(2)

; #define LAS __attribute__((address_space(3)))
; __device__ __forceinline__ void partialSM(f32x16& p0, f32x16& p1, const LAS float* tbp, int relc, float cL, float cR, float& m_reg, float& mn, float& alpha) {
;     float cb = 0.f;
;     if (relc + 63 <= -559) cb = cL;
;     else if (relc - 31 >= 559) cb = cR;
;     else {
; #pragma unroll
;         for (int r = 0; r < 16; ++r) { p0[r] += tbp[(r & 3) + 8 * (r >> 2)]; p1[r] += tbp[32 + (r & 3) + 8 * (r >> 2)]; }
;     }
;     float pmax = p0[0];
; #pragma unroll
;     for (int r = 1; r < 16; ++r) pmax = fmaxf(pmax, p0[r]);
; #pragma unroll
;     for (int r = 0; r < 16; ++r) pmax = fmaxf(pmax, p1[r]);
;     pmax = half_max(pmax) + cb;
;     if (__builtin_expect(__all(pmax - m_reg <= 8.f), 1)) { mn = m_reg; alpha = 1.f; }
;     else { mn = fmaxf(m_reg, pmax); alpha = __builtin_amdgcn_exp2f(m_reg - mn); m_reg = mn; }
;     const float sh = mn - cb;
; #pragma unroll
;     for (int r = 0; r < 16; ++r) { p0[r] -= sh; p1[r] -= sh; }
; #pragma unroll
;     for (int r = 0; r < 16; ++r) p0[r] = __builtin_amdgcn_exp2f(p0[r]);
; }
; template <int D0> __device__ __forceinline__ void pv_one(f32x16& od, int vb, bf16x8 pa0, bf16x8 pa1, bf16x8 pa2, bf16x8 pa3) {
;     s16x4 l0 = tr_read<v_rd_off(D0, 0, 0)>(vb), h0 = tr_read<v_rd_off(D0, 0, 1)>(vb), l1 = tr_read<v_rd_off(D0, 1, 0)>(vb), h1 = tr_read<v_rd_off(D0, 1, 1)>(vb);
;     s16x4 l2 = tr_read<v_rd_off(D0, 2, 0)>(vb), h2 = tr_read<v_rd_off(D0, 2, 1)>(vb), l3 = tr_read<v_rd_off(D0, 3, 0)>(vb), h3 = tr_read<v_rd_off(D0, 3, 1)>(vb);
;     asm volatile("s_waitcnt lgkmcnt(0)" : "+v"(l0), "+v"(h0), "+v"(l1), "+v"(h1), "+v"(l2), "+v"(h2), "+v"(l3), "+v"(h3) :: "memory");
;     od = __builtin_amdgcn_mfma_f32_32x32x16_bf16(pa0, PKV(l0, h0), od, 0, 0, 0);
;     od = __builtin_amdgcn_mfma_f32_32x32x16_bf16(pa1, PKV(l1, h1), od, 0, 0, 0);
;     od = __builtin_amdgcn_mfma_f32_32x32x16_bf16(pa2, PKV(l2, h2), od, 0, 0, 0);
;     od = __builtin_amdgcn_mfma_f32_32x32x16_bf16(pa3, PKV(l3, h3), od, 0, 0, 0);
; }
; __device__ __forceinline__ void pv_d0(f32x16* o, int vb, bf16x8 pa0, bf16x8 pa1, bf16x8 pa2, bf16x8 pa3) {
;     pv_one<0>(o[0], vb, pa0, pa1, pa2, pa3); pv_one<1>(o[1], vb, pa0, pa1, pa2, pa3); pv_one<2>(o[2], vb, pa0, pa1, pa2, pa3); pv_one<3>(o[3], vb, pa0, pa1, pa2, pa3);
; }
.Lmb_pv_h2:
	s_waitcnt lgkmcnt(0)
	v_mfma_f32_32x32x16_bf16 v[0:15], v[80:83], v[88:91], v[0:15]
	ds_read_b64_tr_b16 v[88:89], v186 offset:512
	ds_read_b64_tr_b16 v[90:91], v186 offset:2560
	v_mfma_f32_32x32x16_bf16 v[0:15], v[84:87], v[92:95], v[0:15]
	ds_read_b64_tr_b16 v[92:93], v186 offset:4608
	ds_read_b64_tr_b16 v[94:95], v186 offset:6656
	v_max3_f32 v254, v232, v233, v234
	v_max3_f32 v255, v235, v236, v237
	v_max3_f32 v254, v254, v238, v239
	v_max3_f32 v255, v255, v240, v241
	v_max3_f32 v254, v254, v242, v243
	v_max3_f32 v255, v255, v244, v245
	v_mfma_f32_32x32x16_bf16 v[0:15], v[64:67], v[72:75], v[0:15]
	ds_read_b64_tr_b16 v[72:73], v186 offset:8704
	ds_read_b64_tr_b16 v[74:75], v186 offset:10752
	v_max3_f32 v254, v254, v246, v247
	v_max3_f32 v255, v255, v144, v145
	v_max3_f32 v254, v254, v146, v147
	v_max3_f32 v255, v255, v148, v149
	v_max3_f32 v254, v254, v150, v151
	v_max3_f32 v255, v255, v152, v153
	v_mfma_f32_32x32x16_bf16 v[0:15], v[68:71], v[76:79], v[0:15]
	ds_read_b64_tr_b16 v[76:77], v186 offset:12800
	ds_read_b64_tr_b16 v[78:79], v186 offset:14848
	v_max3_f32 v254, v254, v154, v155
	v_max3_f32 v255, v255, v156, v157
	v_max3_f32 v254, v254, v158, v159
	v_max_f32_e32 v254, v254, v255
	v_mov_b32_e32 v255, v254
	s_waitcnt lgkmcnt(0)
	v_mfma_f32_32x32x16_bf16 v[48:63], v[80:83], v[88:91], v[48:63]
	ds_read_b64_tr_b16 v[88:89], v186 offset:1024
	ds_read_b64_tr_b16 v[90:91], v186 offset:3072
	v_permlane32_swap_b32_e32 v254, v255
	v_max_f32_e32 v254, v254, v255
	v_add_f32_e32 v254, v249, v254
	v_sub_f32_e32 v255, v254, v250
	v_cmp_ge_f32_e32 vcc, s35, v255
	v_max_f32_e32 v255, v250, v254
	v_mfma_f32_32x32x16_bf16 v[48:63], v[84:87], v[92:95], v[48:63]
	ds_read_b64_tr_b16 v[92:93], v186 offset:5120
	ds_read_b64_tr_b16 v[94:95], v186 offset:7168
	v_sub_f32_e32 v248, v250, v255
	v_exp_f32_e32 v248, v248
	v_sub_f32_e32 v252, v255, v249
	v_sub_f32_e32 v254, v250, v249
	s_cmp_eq_u64 vcc, exec
	s_cselect_b64 s[4:5], -1, 0
	v_cndmask_b32_e64 v251, v248, 1.0, s[4:5]
	v_mfma_f32_32x32x16_bf16 v[48:63], v[64:67], v[72:75], v[48:63]
	ds_read_b64_tr_b16 v[72:73], v186 offset:9216
	ds_read_b64_tr_b16 v[74:75], v186 offset:11264
	v_cndmask_b32_e64 v250, v255, v250, s[4:5]
	v_cndmask_b32_e64 v252, v252, v254, s[4:5]
	v_sub_f32_e32 v232, v232, v252
	v_sub_f32_e32 v233, v233, v252
	v_sub_f32_e32 v234, v234, v252
	v_sub_f32_e32 v235, v235, v252
	v_mfma_f32_32x32x16_bf16 v[48:63], v[68:71], v[76:79], v[48:63]
	ds_read_b64_tr_b16 v[76:77], v186 offset:13312
	ds_read_b64_tr_b16 v[78:79], v186 offset:15360
	v_sub_f32_e32 v236, v236, v252
	v_sub_f32_e32 v237, v237, v252
	v_sub_f32_e32 v238, v238, v252
	v_sub_f32_e32 v239, v239, v252
	v_sub_f32_e32 v240, v240, v252
	v_sub_f32_e32 v241, v241, v252
	s_waitcnt lgkmcnt(0)
	v_mfma_f32_32x32x16_bf16 v[32:47], v[80:83], v[88:91], v[32:47]
	ds_read_b64_tr_b16 v[88:89], v186 offset:1536
	ds_read_b64_tr_b16 v[90:91], v186 offset:3584
	v_sub_f32_e32 v242, v242, v252
	v_sub_f32_e32 v243, v243, v252
	v_sub_f32_e32 v244, v244, v252
	v_sub_f32_e32 v245, v245, v252
	v_sub_f32_e32 v246, v246, v252
	v_sub_f32_e32 v247, v247, v252
	v_mfma_f32_32x32x16_bf16 v[32:47], v[84:87], v[92:95], v[32:47]
	ds_read_b64_tr_b16 v[92:93], v186 offset:5632
	ds_read_b64_tr_b16 v[94:95], v186 offset:7680
	v_exp_f32_e32 v232, v232
	v_sub_f32_e32 v144, v144, v252
	v_exp_f32_e32 v233, v233
	v_sub_f32_e32 v145, v145, v252
	v_mfma_f32_32x32x16_bf16 v[32:47], v[64:67], v[72:75], v[32:47]
	ds_read_b64_tr_b16 v[72:73], v186 offset:9728
	ds_read_b64_tr_b16 v[74:75], v186 offset:11776
	v_exp_f32_e32 v234, v234
	v_sub_f32_e32 v146, v146, v252
	v_exp_f32_e32 v235, v235
	v_sub_f32_e32 v147, v147, v252
	v_mfma_f32_32x32x16_bf16 v[32:47], v[68:71], v[76:79], v[32:47]
	ds_read_b64_tr_b16 v[76:77], v186 offset:13824
	ds_read_b64_tr_b16 v[78:79], v186 offset:15872
	v_exp_f32_e32 v236, v236
	v_sub_f32_e32 v148, v148, v252
	v_exp_f32_e32 v237, v237
	v_sub_f32_e32 v149, v149, v252
	s_waitcnt lgkmcnt(0)
	v_mfma_f32_32x32x16_bf16 v[16:31], v[80:83], v[88:91], v[16:31]
	v_exp_f32_e32 v238, v238
	v_sub_f32_e32 v150, v150, v252
	v_exp_f32_e32 v239, v239
	v_sub_f32_e32 v151, v151, v252
	v_mfma_f32_32x32x16_bf16 v[16:31], v[84:87], v[92:95], v[16:31]
	v_exp_f32_e32 v240, v240
	v_sub_f32_e32 v152, v152, v252
	v_exp_f32_e32 v241, v241
	v_sub_f32_e32 v153, v153, v252
	v_mfma_f32_32x32x16_bf16 v[16:31], v[64:67], v[72:75], v[16:31]
	v_exp_f32_e32 v242, v242
	v_sub_f32_e32 v154, v154, v252
	v_exp_f32_e32 v243, v243
	v_sub_f32_e32 v155, v155, v252
	v_mfma_f32_32x32x16_bf16 v[16:31], v[68:71], v[76:79], v[16:31]
	v_exp_f32_e32 v244, v244
	v_sub_f32_e32 v156, v156, v252
	v_exp_f32_e32 v245, v245
	v_sub_f32_e32 v157, v157, v252
	v_exp_f32_e32 v246, v246
	v_sub_f32_e32 v158, v158, v252
	v_exp_f32_e32 v247, v247
	v_sub_f32_e32 v159, v159, v252
	s_barrier
	s_waitcnt vmcnt(4)
	s_and_b64 vcc, exec, s[26:27]
	s_cbranch_vccz .Lmb_w2
	s_waitcnt vmcnt(0)

; #define LAS __attribute__((address_space(3)))
; __device__ __forceinline__ void partialSM(f32x16& p0, f32x16& p1, const LAS float* tbp, int relc, float cL, float cR, float& m_reg, float& mn, float& alpha) {
;     float cb = 0.f;
;     if (relc + 63 <= -559) cb = cL;
;     else if (relc - 31 >= 559) cb = cR;
;     else {
; #pragma unroll
;         for (int r = 0; r < 16; ++r) { p0[r] += tbp[(r & 3) + 8 * (r >> 2)]; p1[r] += tbp[32 + (r & 3) + 8 * (r >> 2)]; }
;     }
;     float pmax = p0[0];
; #pragma unroll
;     for (int r = 1; r < 16; ++r) pmax = fmaxf(pmax, p0[r]);
; #pragma unroll
;     for (int r = 0; r < 16; ++r) pmax = fmaxf(pmax, p1[r]);
;     pmax = half_max(pmax) + cb;
;     if (__builtin_expect(__all(pmax - m_reg <= 8.f), 1)) { mn = m_reg; alpha = 1.f; }
;     else { mn = fmaxf(m_reg, pmax); alpha = __builtin_amdgcn_exp2f(m_reg - mn); m_reg = mn; }
;     const float sh = mn - cb;
; #pragma unroll
;     for (int r = 0; r < 16; ++r) { p0[r] -= sh; p1[r] -= sh; }
; #pragma unroll
;     for (int r = 0; r < 16; ++r) p0[r] = __builtin_amdgcn_exp2f(p0[r]);
; }
; template <int D0> __device__ __forceinline__ void pv_one(f32x16& od, int vb, bf16x8 pa0, bf16x8 pa1, bf16x8 pa2, bf16x8 pa3) {
;     s16x4 l0 = tr_read<v_rd_off(D0, 0, 0)>(vb), h0 = tr_read<v_rd_off(D0, 0, 1)>(vb), l1 = tr_read<v_rd_off(D0, 1, 0)>(vb), h1 = tr_read<v_rd_off(D0, 1, 1)>(vb);
;     s16x4 l2 = tr_read<v_rd_off(D0, 2, 0)>(vb), h2 = tr_read<v_rd_off(D0, 2, 1)>(vb), l3 = tr_read<v_rd_off(D0, 3, 0)>(vb), h3 = tr_read<v_rd_off(D0, 3, 1)>(vb);
;     asm volatile("s_waitcnt lgkmcnt(0)" : "+v"(l0), "+v"(h0), "+v"(l1), "+v"(h1), "+v"(l2), "+v"(h2), "+v"(l3), "+v"(h3) :: "memory");
;     od = __builtin_amdgcn_mfma_f32_32x32x16_bf16(pa0, PKV(l0, h0), od, 0, 0, 0);
;     od = __builtin_amdgcn_mfma_f32_32x32x16_bf16(pa1, PKV(l1, h1), od, 0, 0, 0);
;     od = __builtin_amdgcn_mfma_f32_32x32x16_bf16(pa2, PKV(l2, h2), od, 0, 0, 0);
;     od = __builtin_amdgcn_mfma_f32_32x32x16_bf16(pa3, PKV(l3, h3), od, 0, 0, 0);
; }
; __device__ __forceinline__ void pv_d0(f32x16* o, int vb, bf16x8 pa0, bf16x8 pa1, bf16x8 pa2, bf16x8 pa3) {
;     pv_one<0>(o[0], vb, pa0, pa1, pa2, pa3); pv_one<1>(o[1], vb, pa0, pa1, pa2, pa3); pv_one<2>(o[2], vb, pa0, pa1, pa2, pa3); pv_one<3>(o[3], vb, pa0, pa1, pa2, pa3);
; }
.Lmb_pv_pe:
	s_nop 5
	s_waitcnt lgkmcnt(0)
	v_mfma_f32_32x32x16_bf16 v[0:15], v[232:235], v[240:243], v[0:15]
	ds_read_b64_tr_b16 v[240:241], v175 offset:512
	ds_read_b64_tr_b16 v[242:243], v175 offset:2560
	v_mfma_f32_32x32x16_bf16 v[0:15], v[236:239], v[244:247], v[0:15]
	ds_read_b64_tr_b16 v[244:245], v175 offset:4608
	ds_read_b64_tr_b16 v[246:247], v175 offset:6656
	v_max3_f32 v254, v80, v81, v82
	v_max3_f32 v255, v83, v84, v85
	v_max3_f32 v254, v254, v86, v87
	v_max3_f32 v255, v255, v88, v89
	v_max3_f32 v254, v254, v90, v91
	v_max3_f32 v255, v255, v92, v93
	v_mfma_f32_32x32x16_bf16 v[0:15], v[144:147], v[152:155], v[0:15]
	ds_read_b64_tr_b16 v[152:153], v175 offset:8704
	ds_read_b64_tr_b16 v[154:155], v175 offset:10752
	v_max3_f32 v254, v254, v94, v95
	v_max3_f32 v255, v255, v64, v65
	v_max3_f32 v254, v254, v66, v67
	v_max3_f32 v255, v255, v68, v69
	v_max3_f32 v254, v254, v70, v71
	v_max3_f32 v255, v255, v72, v73
	v_mfma_f32_32x32x16_bf16 v[0:15], v[148:151], v[156:159], v[0:15]
	ds_read_b64_tr_b16 v[156:157], v175 offset:12800
	ds_read_b64_tr_b16 v[158:159], v175 offset:14848
	v_max3_f32 v254, v254, v74, v75
	v_max3_f32 v255, v255, v76, v77
	v_max3_f32 v254, v254, v78, v79
	v_max_f32_e32 v254, v254, v255
	v_mov_b32_e32 v255, v254
	s_waitcnt lgkmcnt(0)
	v_mfma_f32_32x32x16_bf16 v[48:63], v[232:235], v[240:243], v[48:63]
	ds_read_b64_tr_b16 v[240:241], v175 offset:1024
	ds_read_b64_tr_b16 v[242:243], v175 offset:3072
	v_permlane32_swap_b32_e32 v254, v255
	v_max_f32_e32 v254, v254, v255
	v_add_f32_e32 v254, v249, v254
	v_sub_f32_e32 v255, v254, v250
	v_cmp_ge_f32_e32 vcc, s35, v255
	v_max_f32_e32 v255, v250, v254
	v_mfma_f32_32x32x16_bf16 v[48:63], v[236:239], v[244:247], v[48:63]
	ds_read_b64_tr_b16 v[244:245], v175 offset:5120
	ds_read_b64_tr_b16 v[246:247], v175 offset:7168
	v_sub_f32_e32 v248, v250, v255
	v_exp_f32_e32 v248, v248
	v_sub_f32_e32 v252, v255, v249
	v_sub_f32_e32 v254, v250, v249
	s_cmp_eq_u64 vcc, exec
	s_cselect_b64 s[4:5], -1, 0
	v_cndmask_b32_e64 v251, v248, 1.0, s[4:5]
	v_mfma_f32_32x32x16_bf16 v[48:63], v[144:147], v[152:155], v[48:63]
	ds_read_b64_tr_b16 v[152:153], v175 offset:9216
	ds_read_b64_tr_b16 v[154:155], v175 offset:11264
	v_cndmask_b32_e64 v250, v255, v250, s[4:5]
	v_cndmask_b32_e64 v252, v252, v254, s[4:5]
	v_sub_f32_e32 v80, v80, v252
	v_sub_f32_e32 v81, v81, v252
	v_sub_f32_e32 v82, v82, v252
	v_sub_f32_e32 v83, v83, v252
	v_mfma_f32_32x32x16_bf16 v[48:63], v[148:151], v[156:159], v[48:63]
	ds_read_b64_tr_b16 v[156:157], v175 offset:13312
	ds_read_b64_tr_b16 v[158:159], v175 offset:15360
	v_sub_f32_e32 v84, v84, v252
	v_sub_f32_e32 v85, v85, v252
	v_sub_f32_e32 v86, v86, v252
	v_sub_f32_e32 v87, v87, v252
	v_sub_f32_e32 v88, v88, v252
	v_sub_f32_e32 v89, v89, v252
	s_waitcnt lgkmcnt(0)
	v_mfma_f32_32x32x16_bf16 v[32:47], v[232:235], v[240:243], v[32:47]
	ds_read_b64_tr_b16 v[240:241], v175 offset:1536
	ds_read_b64_tr_b16 v[242:243], v175 offset:3584
	v_sub_f32_e32 v90, v90, v252
	v_sub_f32_e32 v91, v91, v252
	v_sub_f32_e32 v92, v92, v252
	v_sub_f32_e32 v93, v93, v252
	v_sub_f32_e32 v94, v94, v252
	v_sub_f32_e32 v95, v95, v252
	v_mfma_f32_32x32x16_bf16 v[32:47], v[236:239], v[244:247], v[32:47]
	ds_read_b64_tr_b16 v[244:245], v175 offset:5632
	ds_read_b64_tr_b16 v[246:247], v175 offset:7680
	v_exp_f32_e32 v80, v80
	v_sub_f32_e32 v64, v64, v252
	v_exp_f32_e32 v81, v81
	v_sub_f32_e32 v65, v65, v252
	v_mfma_f32_32x32x16_bf16 v[32:47], v[144:147], v[152:155], v[32:47]
	ds_read_b64_tr_b16 v[152:153], v175 offset:9728
	ds_read_b64_tr_b16 v[154:155], v175 offset:11776
	v_exp_f32_e32 v82, v82
	v_sub_f32_e32 v66, v66, v252
	v_exp_f32_e32 v83, v83
	v_sub_f32_e32 v67, v67, v252
	v_mfma_f32_32x32x16_bf16 v[32:47], v[148:151], v[156:159], v[32:47]
	ds_read_b64_tr_b16 v[156:157], v175 offset:13824
	ds_read_b64_tr_b16 v[158:159], v175 offset:15872
	v_exp_f32_e32 v84, v84
	v_sub_f32_e32 v68, v68, v252
	v_exp_f32_e32 v85, v85
	v_sub_f32_e32 v69, v69, v252
	s_waitcnt lgkmcnt(0)
	v_mfma_f32_32x32x16_bf16 v[16:31], v[232:235], v[240:243], v[16:31]
	v_exp_f32_e32 v86, v86
	v_sub_f32_e32 v70, v70, v252
	v_exp_f32_e32 v87, v87
	v_sub_f32_e32 v71, v71, v252
	v_mfma_f32_32x32x16_bf16 v[16:31], v[236:239], v[244:247], v[16:31]
	v_exp_f32_e32 v88, v88
	v_sub_f32_e32 v72, v72, v252
	v_exp_f32_e32 v89, v89
	v_sub_f32_e32 v73, v73, v252
	v_mfma_f32_32x32x16_bf16 v[16:31], v[144:147], v[152:155], v[16:31]
	v_exp_f32_e32 v90, v90
	v_sub_f32_e32 v74, v74, v252
	v_exp_f32_e32 v91, v91
	v_sub_f32_e32 v75, v75, v252
	v_mfma_f32_32x32x16_bf16 v[16:31], v[148:151], v[156:159], v[16:31]
	v_exp_f32_e32 v92, v92
	v_sub_f32_e32 v76, v76, v252
	v_exp_f32_e32 v93, v93
	v_sub_f32_e32 v77, v77, v252
	v_exp_f32_e32 v94, v94
	v_sub_f32_e32 v78, v78, v252
	v_exp_f32_e32 v95, v95
	v_sub_f32_e32 v79, v79, v252
	s_waitcnt lgkmcnt(0)
	s_barrier
	s_and_b64 vcc, exec, s[4:5]
	s_cbranch_vccnz .Lmb_nr_pe
	s_and_saveexec_b64 s[28:29], s[0:1]
	ds_write_b32 v215, v251 offset:128
	s_or_b64 exec, exec, s[28:29]
	s_waitcnt lgkmcnt(0)
	ds_read_b128 v[112:115], v179 offset:224
	ds_read_b128 v[116:119], v179 offset:192
	ds_read_b128 v[120:123], v179 offset:160
	ds_read_b128 v[124:127], v179 offset:128
	s_waitcnt lgkmcnt(0)
	s_nop 3
	v_pk_mul_f32 v[14:15], v[14:15], v[114:115]
	v_pk_mul_f32 v[12:13], v[12:13], v[112:113]
	v_pk_mul_f32 v[10:11], v[10:11], v[118:119]
	v_pk_mul_f32 v[8:9], v[8:9], v[116:117]
	v_pk_mul_f32 v[6:7], v[6:7], v[122:123]
	v_pk_mul_f32 v[4:5], v[4:5], v[120:121]
	v_pk_mul_f32 v[2:3], v[2:3], v[126:127]
	v_pk_mul_f32 v[0:1], v[0:1], v[124:125]
	v_pk_mul_f32 v[62:63], v[62:63], v[114:115]
	v_pk_mul_f32 v[60:61], v[60:61], v[112:113]
	v_pk_mul_f32 v[58:59], v[58:59], v[118:119]
	v_pk_mul_f32 v[56:57], v[56:57], v[116:117]
	v_pk_mul_f32 v[54:55], v[54:55], v[122:123]
	v_pk_mul_f32 v[52:53], v[52:53], v[120:121]
	v_pk_mul_f32 v[50:51], v[50:51], v[126:127]
	v_pk_mul_f32 v[48:49], v[48:49], v[124:125]
	v_pk_mul_f32 v[46:47], v[46:47], v[114:115]
	v_pk_mul_f32 v[44:45], v[44:45], v[112:113]
	v_pk_mul_f32 v[42:43], v[42:43], v[118:119]
	v_pk_mul_f32 v[40:41], v[40:41], v[116:117]
	v_pk_mul_f32 v[38:39], v[38:39], v[122:123]
	v_pk_mul_f32 v[36:37], v[36:37], v[120:121]
	v_pk_mul_f32 v[34:35], v[34:35], v[126:127]
	v_pk_mul_f32 v[32:33], v[32:33], v[124:125]
	v_pk_mul_f32 v[30:31], v[30:31], v[114:115]
	v_pk_mul_f32 v[28:29], v[28:29], v[112:113]
	v_pk_mul_f32 v[26:27], v[26:27], v[118:119]
	v_pk_mul_f32 v[24:25], v[24:25], v[116:117]
	v_pk_mul_f32 v[22:23], v[22:23], v[122:123]
	v_pk_mul_f32 v[20:21], v[20:21], v[120:121]
	v_pk_mul_f32 v[18:19], v[18:19], v[126:127]
	v_pk_mul_f32 v[16:17], v[16:17], v[124:125]
